# k2: after the own-diagonal f32 K/V cache stores the next-tile LDS staging no longer drains vmcnt (stores stay in flight)
# baseline (speedup 1.0000x reference)
.LBB2_61:
	s_add_i32 s0, s89, s94
	s_cmp_eq_u32 s0, 3
	s_cselect_b64 s[0:1], -1, 0
	s_and_b64 s[0:1], s[72:73], s[0:1]
	s_andn2_b64 vcc, exec, s[0:1]
	s_cbranch_vccnz .LBB2_63
	v_lshl_add_u64 v[38:39], v[164:165], 0, v[142:143]
	v_add_co_u32_e32 v40, vcc, 0x20000, v38
	s_waitcnt vmcnt(3)
	v_lshlrev_b32_e32 v34, 16, v82
	v_and_b32_e32 v35, 0xffff0000, v82
	v_lshlrev_b32_e32 v36, 16, v83
	v_and_b32_e32 v37, 0xffff0000, v83
	v_addc_co_u32_e32 v41, vcc, 0, v39, vcc
	s_mov_b32 s0, 0x30000
	global_store_dwordx4 v[40:41], v[34:37], off
	v_add_co_u32_e32 v38, vcc, s0, v38
	s_nop 0
	v_lshlrev_b32_e32 v34, 16, v84
	v_and_b32_e32 v35, 0xffff0000, v84
	v_lshlrev_b32_e32 v36, 16, v85
	v_and_b32_e32 v37, 0xffff0000, v85
	global_store_dwordx4 v[40:41], v[34:37], off offset:16
	v_addc_co_u32_e32 v39, vcc, 0, v39, vcc
	s_waitcnt vmcnt(4)
	v_lshlrev_b32_e32 v34, 16, v86
	v_and_b32_e32 v35, 0xffff0000, v86
	v_lshlrev_b32_e32 v36, 16, v87
	v_and_b32_e32 v37, 0xffff0000, v87
	global_store_dwordx4 v[38:39], v[34:37], off
	s_mov_b32 s0, 0x20000
	s_nop 0
	v_lshlrev_b32_e32 v34, 16, v88
	v_and_b32_e32 v35, 0xffff0000, v88
	v_lshlrev_b32_e32 v36, 16, v89
	v_and_b32_e32 v37, 0xffff0000, v89
	global_store_dwordx4 v[38:39], v[34:37], off offset:16
	v_lshl_add_u64 v[38:39], v[148:149], 0, v[142:143]
	v_add_co_u32_e32 v40, vcc, s0, v38
	s_waitcnt vmcnt(5)
	v_lshlrev_b32_e32 v34, 16, v90
	v_and_b32_e32 v35, 0xffff0000, v90
	v_lshlrev_b32_e32 v36, 16, v91
	v_and_b32_e32 v37, 0xffff0000, v91
	v_addc_co_u32_e32 v41, vcc, 0, v39, vcc
	global_store_dwordx4 v[40:41], v[34:37], off
	v_add_co_u32_e32 v38, vcc, 0x30000, v38
	s_nop 0
	v_lshlrev_b32_e32 v34, 16, v92
	v_and_b32_e32 v35, 0xffff0000, v92
	v_lshlrev_b32_e32 v36, 16, v93
	v_and_b32_e32 v37, 0xffff0000, v93
	global_store_dwordx4 v[40:41], v[34:37], off offset:16
	v_addc_co_u32_e32 v39, vcc, 0, v39, vcc
	s_waitcnt vmcnt(6)
	v_lshlrev_b32_e32 v34, 16, v94
	v_and_b32_e32 v35, 0xffff0000, v94
	v_lshlrev_b32_e32 v36, 16, v95
	v_and_b32_e32 v37, 0xffff0000, v95
	global_store_dwordx4 v[38:39], v[34:37], off
	s_nop 1
	v_lshlrev_b32_e32 v34, 16, v96
	v_and_b32_e32 v35, 0xffff0000, v96
	v_lshlrev_b32_e32 v36, 16, v97
	v_and_b32_e32 v37, 0xffff0000, v97
	global_store_dwordx4 v[38:39], v[34:37], off offset:16
	s_nop 1
	v_add_u32_e32 v34, v132, v128
	ds_write_b128 v34, v[82:85] offset:17408
	ds_write_b128 v34, v[86:89] offset:26112
	ds_write_b128 v133, v[90:93]
	ds_write_b128 v133, v[94:97] offset:10240
	s_and_saveexec_b64 s[0:1], s[4:5]
	ds_write_b32 v179, v127
	s_or_b64 exec, exec, s[0:1]
	s_branch .LBB2_66

.LBB2_87:
	s_add_i32 s0, s91, s94
	s_cmp_eq_u32 s0, 3
	s_cselect_b64 s[0:1], -1, 0
	s_and_b64 s[0:1], s[72:73], s[0:1]
	s_andn2_b64 vcc, exec, s[0:1]
	s_cbranch_vccnz .LBB2_89
	s_waitcnt vmcnt(3)
	v_lshlrev_b32_e32 v34, 16, v102
	v_and_b32_e32 v35, 0xffff0000, v102
	v_lshlrev_b32_e32 v36, 16, v103
	v_and_b32_e32 v37, 0xffff0000, v103
	global_store_dwordx4 v[138:139], v[34:37], off
	s_nop 1
	v_lshlrev_b32_e32 v34, 16, v104
	v_and_b32_e32 v35, 0xffff0000, v104
	v_lshlrev_b32_e32 v36, 16, v105
	v_and_b32_e32 v37, 0xffff0000, v105
	global_store_dwordx4 v[138:139], v[34:37], off offset:16
	s_waitcnt vmcnt(4)
	s_nop 0
	v_lshlrev_b32_e32 v34, 16, v106
	v_and_b32_e32 v35, 0xffff0000, v106
	v_lshlrev_b32_e32 v36, 16, v107
	v_and_b32_e32 v37, 0xffff0000, v107
	global_store_dwordx4 v[140:141], v[34:37], off
	s_nop 1
	v_lshlrev_b32_e32 v34, 16, v108
	v_and_b32_e32 v35, 0xffff0000, v108
	v_lshlrev_b32_e32 v36, 16, v109
	v_and_b32_e32 v37, 0xffff0000, v109
	global_store_dwordx4 v[140:141], v[34:37], off offset:16
	s_waitcnt vmcnt(5)
	s_nop 0
	v_lshlrev_b32_e32 v34, 16, v110
	v_and_b32_e32 v35, 0xffff0000, v110
	v_lshlrev_b32_e32 v36, 16, v111
	v_and_b32_e32 v37, 0xffff0000, v111
	global_store_dwordx4 v[134:135], v[34:37], off
	s_nop 1
	v_lshlrev_b32_e32 v34, 16, v112
	v_and_b32_e32 v35, 0xffff0000, v112
	v_lshlrev_b32_e32 v36, 16, v113
	v_and_b32_e32 v37, 0xffff0000, v113
	global_store_dwordx4 v[134:135], v[34:37], off offset:16
	s_waitcnt vmcnt(6)
	s_nop 0
	v_lshlrev_b32_e32 v34, 16, v114
	v_and_b32_e32 v35, 0xffff0000, v114
	v_lshlrev_b32_e32 v36, 16, v115
	v_and_b32_e32 v37, 0xffff0000, v115
	global_store_dwordx4 v[136:137], v[34:37], off
	s_nop 1
	v_lshlrev_b32_e32 v34, 16, v116
	v_and_b32_e32 v35, 0xffff0000, v116
	v_lshlrev_b32_e32 v36, 16, v117
	v_and_b32_e32 v37, 0xffff0000, v117
	global_store_dwordx4 v[136:137], v[34:37], off offset:16
	ds_write_b128 v131, v[102:105]
	ds_write_b128 v131, v[106:109] offset:8704
	ds_write_b128 v174, v[110:113] offset:34816
	ds_write_b128 v174, v[114:117] offset:45056
	s_and_saveexec_b64 s[0:1], s[4:5]
	ds_write_b32 v182, v184
	s_or_b64 exec, exec, s[0:1]
	s_branch .LBB2_92

.LBB2_141:
	s_add_i32 s0, s22, s19
	s_cmp_eq_u32 s0, 3
	s_cselect_b64 s[0:1], -1, 0
	s_and_b64 s[0:1], s[6:7], s[0:1]
	s_andn2_b64 vcc, exec, s[0:1]
	s_cbranch_vccnz .LBB2_143
	v_lshl_add_u64 v[70:71], v[222:223], 0, v[202:203]
	v_add_co_u32_e32 v72, vcc, 0x20000, v70
	s_waitcnt vmcnt(3)
	v_lshlrev_b32_e32 v66, 16, v118
	v_and_b32_e32 v67, 0xffff0000, v118
	v_lshlrev_b32_e32 v68, 16, v119
	v_and_b32_e32 v69, 0xffff0000, v119
	v_addc_co_u32_e32 v73, vcc, 0, v71, vcc
	s_mov_b32 s0, 0x30000
	global_store_dwordx4 v[72:73], v[66:69], off
	v_add_co_u32_e32 v70, vcc, s0, v70
	s_nop 0
	v_lshlrev_b32_e32 v66, 16, v120
	v_and_b32_e32 v67, 0xffff0000, v120
	v_lshlrev_b32_e32 v68, 16, v121
	v_and_b32_e32 v69, 0xffff0000, v121
	global_store_dwordx4 v[72:73], v[66:69], off offset:16
	v_addc_co_u32_e32 v71, vcc, 0, v71, vcc
	s_waitcnt vmcnt(4)
	v_lshlrev_b32_e32 v66, 16, v122
	v_and_b32_e32 v67, 0xffff0000, v122
	v_lshlrev_b32_e32 v68, 16, v123
	v_and_b32_e32 v69, 0xffff0000, v123
	global_store_dwordx4 v[70:71], v[66:69], off
	s_mov_b32 s0, 0x20000
	s_nop 0
	v_lshlrev_b32_e32 v66, 16, v124
	v_and_b32_e32 v67, 0xffff0000, v124
	v_lshlrev_b32_e32 v68, 16, v125
	v_and_b32_e32 v69, 0xffff0000, v125
	global_store_dwordx4 v[70:71], v[66:69], off offset:16
	v_lshl_add_u64 v[70:71], v[220:221], 0, v[202:203]
	v_add_co_u32_e32 v72, vcc, s0, v70
	s_waitcnt vmcnt(5)
	v_lshlrev_b32_e32 v66, 16, v126
	v_and_b32_e32 v67, 0xffff0000, v126
	v_lshlrev_b32_e32 v68, 16, v127
	v_and_b32_e32 v69, 0xffff0000, v127
	v_addc_co_u32_e32 v73, vcc, 0, v71, vcc
	global_store_dwordx4 v[72:73], v[66:69], off
	v_add_co_u32_e32 v70, vcc, 0x30000, v70
	s_nop 0
	v_lshlrev_b32_e32 v66, 16, v128
	v_and_b32_e32 v67, 0xffff0000, v128
	v_lshlrev_b32_e32 v68, 16, v129
	v_and_b32_e32 v69, 0xffff0000, v129
	global_store_dwordx4 v[72:73], v[66:69], off offset:16
	v_addc_co_u32_e32 v71, vcc, 0, v71, vcc
	s_waitcnt vmcnt(6)
	v_lshlrev_b32_e32 v66, 16, v130
	v_and_b32_e32 v67, 0xffff0000, v130
	v_lshlrev_b32_e32 v68, 16, v131
	v_and_b32_e32 v69, 0xffff0000, v131
	global_store_dwordx4 v[70:71], v[66:69], off
	s_nop 1
	v_lshlrev_b32_e32 v66, 16, v132
	v_and_b32_e32 v67, 0xffff0000, v132
	v_lshlrev_b32_e32 v68, 16, v133
	v_and_b32_e32 v69, 0xffff0000, v133
	global_store_dwordx4 v[70:71], v[66:69], off offset:16
	s_nop 1
	v_add_u32_e32 v66, v188, v243
	ds_write_b128 v66, v[118:121] offset:17408
	ds_write_b128 v66, v[122:125] offset:26112
	ds_write_b128 v189, v[126:129]
	ds_write_b128 v189, v[130:133] offset:10240
	s_branch .LBB2_144

.LBB2_163:
	s_add_i32 s0, s16, s19
	s_cmp_eq_u32 s0, 3
	s_cselect_b64 s[0:1], -1, 0
	s_and_b64 s[0:1], s[6:7], s[0:1]
	s_andn2_b64 vcc, exec, s[0:1]
	s_cbranch_vccnz .LBB2_165
	s_waitcnt vmcnt(3)
	v_lshlrev_b32_e32 v66, 16, v134
	v_and_b32_e32 v67, 0xffff0000, v134
	v_lshlrev_b32_e32 v68, 16, v135
	v_and_b32_e32 v69, 0xffff0000, v135
	global_store_dwordx4 v[190:191], v[66:69], off
	s_nop 1
	v_lshlrev_b32_e32 v66, 16, v136
	v_and_b32_e32 v67, 0xffff0000, v136
	v_lshlrev_b32_e32 v68, 16, v137
	v_and_b32_e32 v69, 0xffff0000, v137
	global_store_dwordx4 v[190:191], v[66:69], off offset:16
	s_waitcnt vmcnt(4)
	s_nop 0
	v_lshlrev_b32_e32 v66, 16, v138
	v_and_b32_e32 v67, 0xffff0000, v138
	v_lshlrev_b32_e32 v68, 16, v139
	v_and_b32_e32 v69, 0xffff0000, v139
	global_store_dwordx4 v[232:233], v[66:69], off
	s_nop 1
	v_lshlrev_b32_e32 v66, 16, v140
	v_and_b32_e32 v67, 0xffff0000, v140
	v_lshlrev_b32_e32 v68, 16, v141
	v_and_b32_e32 v69, 0xffff0000, v141
	global_store_dwordx4 v[232:233], v[66:69], off offset:16
	s_waitcnt vmcnt(5)
	s_nop 0
	v_lshlrev_b32_e32 v66, 16, v142
	v_and_b32_e32 v67, 0xffff0000, v142
	v_lshlrev_b32_e32 v68, 16, v143
	v_and_b32_e32 v69, 0xffff0000, v143
	global_store_dwordx4 v[192:193], v[66:69], off
	s_nop 1
	v_lshlrev_b32_e32 v66, 16, v144
	v_and_b32_e32 v67, 0xffff0000, v144
	v_lshlrev_b32_e32 v68, 16, v145
	v_and_b32_e32 v69, 0xffff0000, v145
	global_store_dwordx4 v[192:193], v[66:69], off offset:16
	s_waitcnt vmcnt(6)
	s_nop 0
	v_lshlrev_b32_e32 v66, 16, v146
	v_and_b32_e32 v67, 0xffff0000, v146
	v_lshlrev_b32_e32 v68, 16, v147
	v_and_b32_e32 v69, 0xffff0000, v147
	global_store_dwordx4 v[234:235], v[66:69], off
	s_nop 1
	v_lshlrev_b32_e32 v66, 16, v148
	v_and_b32_e32 v67, 0xffff0000, v148
	v_lshlrev_b32_e32 v68, 16, v149
	v_and_b32_e32 v69, 0xffff0000, v149
	global_store_dwordx4 v[234:235], v[66:69], off offset:16
	ds_write_b128 v244, v[134:137]
	ds_write_b128 v244, v[138:141] offset:8704
	ds_write_b128 v245, v[142:145] offset:34816
	ds_write_b128 v245, v[146:149] offset:45056
	s_branch .LBB2_166
